# hyena conv1 (M1 task) epilogue loads hoisted as well
# speedup vs baseline: 1.0155x; 1.0020x over previous
.LBB0_1070:
	v_div_scale_f32 v0, s[14:15], v42, v42, 1.0
	v_rcp_f32_e32 v34, v0
	s_load_dwordx2 s[14:15], s[16:17], 0x90
	v_readlane_b32 s2, v255, 52
	s_or_b32 s4, s6, s2
	v_fma_f32 v35, -v0, v34, 1.0
	v_fmac_f32_e32 v34, v35, v34
	v_div_scale_f32 v35, vcc, 1.0, v42, 1.0
	s_lshl_b64 s[16:17], s[4:5], 2
	v_mul_f32_e32 v36, v35, v34
	s_waitcnt lgkmcnt(0)
	s_add_u32 s14, s14, s16
	v_fma_f32 v37, -v0, v36, v35
	s_addc_u32 s15, s15, s17
	v_fmac_f32_e32 v36, v37, v34
	s_add_u32 s16, s46, 0x900000
	v_fma_f32 v0, -v0, v36, v35
	s_addc_u32 s17, s47, 0
	v_div_fmas_f32 v0, v0, v34, v36
	global_load_dword v36, v1, s[14:15]
	s_and_b64 s[14:15], s[18:19], exec
	v_div_fixup_f32 v34, v0, v42, 1.0
	v_lshlrev_b32_e32 v0, 2, v38
	s_cselect_b32 s2, 11, 8
	v_or3_b32 v38, v0, v41, v40
	v_lshlrev_b32_e32 v0, s2, v39
	v_or_b32_e32 v0, s7, v0
	v_ashrrev_i32_e32 v39, 31, v38
	v_lshl_add_u64 v[40:41], v[0:1], 0, v[38:39]
	v_lshlrev_b64 v[40:41], 1, v[40:41]
	v_lshl_add_u64 v[44:45], s[16:17], 0, v[40:41]
	v_lshl_add_u64 v[42:43], s[46:47], 0, v[40:41]
	global_load_dwordx2 v[142:143], v[42:43], off offset:16
	global_load_dwordx2 v[144:145], v[44:45], off offset:16
	global_load_dwordx2 v[146:147], v[42:43], off offset:32
	global_load_dwordx2 v[148:149], v[44:45], off offset:32
	global_load_dwordx2 v[150:151], v[42:43], off offset:48
	global_load_dwordx2 v[152:153], v[44:45], off offset:48
	global_load_dwordx2 v[154:155], v[42:43], off offset:2048
	global_load_dwordx2 v[156:157], v[44:45], off offset:2048
	global_load_dwordx2 v[158:159], v[42:43], off offset:2064
	global_load_dwordx2 v[160:161], v[44:45], off offset:2064
	global_load_dwordx2 v[162:163], v[42:43], off offset:2080
	global_load_dwordx2 v[164:165], v[44:45], off offset:2080
	global_load_dwordx2 v[166:167], v[42:43], off offset:2096
	global_load_dwordx2 v[168:169], v[44:45], off offset:2096
	global_load_dwordx2 v[44:45], v[44:45], off
	s_nop 0
	global_load_dwordx2 v[46:47], v[42:43], off
	v_mov_b32_e32 v52, v18
	v_mov_b32_e32 v53, v20
	v_mov_b32_e32 v20, v19
	s_add_u32 s2, s50, s10
	s_addc_u32 s3, s51, 0
	s_add_u32 s18, s2, 0xde35800
	s_addc_u32 s19, s3, 0
	v_lshl_add_u64 v[40:41], s[18:19], 0, v[40:41]
	s_waitcnt vmcnt(0)
	v_lshlrev_b32_e32 v49, 16, v45
	v_lshlrev_b32_e32 v51, 16, v47
	v_lshlrev_b32_e32 v50, 16, v46
	v_and_b32_e32 v47, 0xffff0000, v47
	v_and_b32_e32 v46, 0xffff0000, v46
	v_pk_mul_f32 v[18:19], v[36:37], v[46:47] op_sel_hi:[0,1]
	v_lshlrev_b32_e32 v48, 16, v44
	v_and_b32_e32 v45, 0xffff0000, v45
	v_and_b32_e32 v44, 0xffff0000, v44
	v_pk_mul_f32 v[50:51], v[36:37], v[50:51] op_sel_hi:[0,1]
	v_pk_fma_f32 v[18:19], v[34:35], v[20:21], v[18:19] op_sel_hi:[0,1,1]
	v_pk_fma_f32 v[50:51], v[34:35], v[52:53], v[50:51] op_sel_hi:[0,1,1]
	v_pk_mul_f32 v[18:19], v[18:19], v[44:45]
	v_pk_mul_f32 v[48:49], v[50:51], v[48:49]
	v_and_b32_sdwa v35, v19, v177 dst_sel:DWORD dst_unused:UNUSED_PAD src0_sel:WORD_1 src1_sel:DWORD
	v_and_b32_sdwa v37, v18, v177 dst_sel:DWORD dst_unused:UNUSED_PAD src0_sel:WORD_1 src1_sel:DWORD
	v_and_b32_sdwa v20, v49, v177 dst_sel:DWORD dst_unused:UNUSED_PAD src0_sel:WORD_1 src1_sel:DWORD
	v_and_b32_sdwa v21, v48, v177 dst_sel:DWORD dst_unused:UNUSED_PAD src0_sel:WORD_1 src1_sel:DWORD
	v_add3_u32 v19, v19, v35, s28
	v_add3_u32 v18, v18, v37, s28
	v_add3_u32 v21, v48, v21, s28
	v_add3_u32 v20, v49, v20, s28
	v_and_b32_e32 v19, 0xffff0000, v19
	v_and_b32_e32 v18, 0xffff0000, v18
	v_or_b32_sdwa v19, v19, v20 dst_sel:DWORD dst_unused:UNUSED_PAD src0_sel:DWORD src1_sel:WORD_1
	v_or_b32_sdwa v18, v18, v21 dst_sel:DWORD dst_unused:UNUSED_PAD src0_sel:DWORD src1_sel:WORD_1
	global_store_dwordx2 v[40:41], v[18:19], off
	v_or_b32_e32 v18, 8, v38
	v_ashrrev_i32_e32 v19, 31, v18
	v_lshl_add_u64 v[18:19], v[0:1], 0, v[18:19]
	v_lshl_add_u64 v[18:19], v[18:19], 1, s[16:17]
	v_mov_b32_e32 v18, v144
	v_mov_b32_e32 v19, v145
	s_nop 0
	v_mov_b32_e32 v20, v142
	v_mov_b32_e32 v21, v143
	v_mov_b32_e32 v49, v24
	v_mov_b32_e32 v24, v23
	v_mov_b32_e32 v48, v22
	v_lshlrev_b32_e32 v45, 16, v19
	v_lshlrev_b32_e32 v47, 16, v21
	v_lshlrev_b32_e32 v46, 16, v20
	v_and_b32_e32 v21, 0xffff0000, v21
	v_and_b32_e32 v20, 0xffff0000, v20
	v_pk_mul_f32 v[20:21], v[36:37], v[20:21] op_sel_hi:[0,1]
	v_lshlrev_b32_e32 v44, 16, v18
	v_and_b32_e32 v19, 0xffff0000, v19
	v_and_b32_e32 v18, 0xffff0000, v18
	v_pk_mul_f32 v[46:47], v[36:37], v[46:47] op_sel_hi:[0,1]
	v_pk_fma_f32 v[20:21], v[34:35], v[24:25], v[20:21] op_sel_hi:[0,1,1]
	v_pk_fma_f32 v[46:47], v[34:35], v[48:49], v[46:47] op_sel_hi:[0,1,1]
	v_pk_mul_f32 v[18:19], v[20:21], v[18:19]
	v_pk_mul_f32 v[44:45], v[46:47], v[44:45]
	v_and_b32_sdwa v22, v19, v177 dst_sel:DWORD dst_unused:UNUSED_PAD src0_sel:WORD_1 src1_sel:DWORD
	v_and_b32_sdwa v23, v18, v177 dst_sel:DWORD dst_unused:UNUSED_PAD src0_sel:WORD_1 src1_sel:DWORD
	v_and_b32_sdwa v20, v45, v177 dst_sel:DWORD dst_unused:UNUSED_PAD src0_sel:WORD_1 src1_sel:DWORD
	v_and_b32_sdwa v21, v44, v177 dst_sel:DWORD dst_unused:UNUSED_PAD src0_sel:WORD_1 src1_sel:DWORD
	v_add3_u32 v19, v19, v22, s28
	v_add3_u32 v18, v18, v23, s28
	v_add3_u32 v21, v44, v21, s28
	v_add3_u32 v20, v45, v20, s28
	v_and_b32_e32 v19, 0xffff0000, v19
	v_and_b32_e32 v18, 0xffff0000, v18
	v_or_b32_sdwa v19, v19, v20 dst_sel:DWORD dst_unused:UNUSED_PAD src0_sel:DWORD src1_sel:WORD_1
	v_or_b32_sdwa v18, v18, v21 dst_sel:DWORD dst_unused:UNUSED_PAD src0_sel:DWORD src1_sel:WORD_1
	global_store_dwordx2 v[40:41], v[18:19], off offset:16
	v_or_b32_e32 v18, 16, v38
	v_ashrrev_i32_e32 v19, 31, v18
	v_lshl_add_u64 v[18:19], v[0:1], 0, v[18:19]
	v_lshl_add_u64 v[18:19], v[18:19], 1, s[16:17]
	v_mov_b32_e32 v18, v148
	v_mov_b32_e32 v19, v149
	s_nop 0
	v_mov_b32_e32 v20, v146
	v_mov_b32_e32 v21, v147
	v_mov_b32_e32 v44, v26
	v_mov_b32_e32 v45, v28
	v_mov_b32_e32 v28, v27
	v_mov_b32_e32 v26, v30
	v_mov_b32_e32 v27, v32
	v_mov_b32_e32 v32, v31
	v_lshlrev_b32_e32 v23, 16, v19
	v_lshlrev_b32_e32 v25, 16, v21
	v_lshlrev_b32_e32 v24, 16, v20
	v_and_b32_e32 v21, 0xffff0000, v21
	v_and_b32_e32 v20, 0xffff0000, v20
	v_pk_mul_f32 v[24:25], v[36:37], v[24:25] op_sel_hi:[0,1]
	v_lshlrev_b32_e32 v22, 16, v18
	v_pk_fma_f32 v[24:25], v[34:35], v[44:45], v[24:25] op_sel_hi:[0,1,1]
	v_pk_mul_f32 v[20:21], v[36:37], v[20:21] op_sel_hi:[0,1]
	v_and_b32_e32 v19, 0xffff0000, v19
	v_and_b32_e32 v18, 0xffff0000, v18
	v_pk_mul_f32 v[22:23], v[24:25], v[22:23]
	v_pk_fma_f32 v[20:21], v[34:35], v[28:29], v[20:21] op_sel_hi:[0,1,1]
	v_pk_mul_f32 v[18:19], v[20:21], v[18:19]
	v_and_b32_sdwa v20, v23, v177 dst_sel:DWORD dst_unused:UNUSED_PAD src0_sel:WORD_1 src1_sel:DWORD
	v_and_b32_sdwa v21, v22, v177 dst_sel:DWORD dst_unused:UNUSED_PAD src0_sel:WORD_1 src1_sel:DWORD
	v_add3_u32 v21, v22, v21, s28
	v_add3_u32 v20, v23, v20, s28
	v_and_b32_sdwa v22, v19, v177 dst_sel:DWORD dst_unused:UNUSED_PAD src0_sel:WORD_1 src1_sel:DWORD
	v_and_b32_sdwa v23, v18, v177 dst_sel:DWORD dst_unused:UNUSED_PAD src0_sel:WORD_1 src1_sel:DWORD
	v_add3_u32 v19, v19, v22, s28
	v_add3_u32 v18, v18, v23, s28
	v_and_b32_e32 v19, 0xffff0000, v19
	v_and_b32_e32 v18, 0xffff0000, v18
	v_or_b32_sdwa v19, v19, v20 dst_sel:DWORD dst_unused:UNUSED_PAD src0_sel:DWORD src1_sel:WORD_1
	v_or_b32_sdwa v18, v18, v21 dst_sel:DWORD dst_unused:UNUSED_PAD src0_sel:DWORD src1_sel:WORD_1
	global_store_dwordx2 v[40:41], v[18:19], off offset:32
	v_or_b32_e32 v18, 24, v38
	v_ashrrev_i32_e32 v19, 31, v18
	v_lshl_add_u64 v[18:19], v[0:1], 0, v[18:19]
	v_lshl_add_u64 v[18:19], v[18:19], 1, s[16:17]
	v_mov_b32_e32 v18, v152
	v_mov_b32_e32 v19, v153
	s_nop 0
	v_mov_b32_e32 v20, v150
	v_mov_b32_e32 v21, v151
	v_lshlrev_b32_e32 v23, 16, v19
	v_lshlrev_b32_e32 v25, 16, v21
	v_lshlrev_b32_e32 v24, 16, v20
	v_and_b32_e32 v21, 0xffff0000, v21
	v_and_b32_e32 v20, 0xffff0000, v20
	v_pk_mul_f32 v[24:25], v[36:37], v[24:25] op_sel_hi:[0,1]
	v_lshlrev_b32_e32 v22, 16, v18
	v_pk_fma_f32 v[24:25], v[34:35], v[26:27], v[24:25] op_sel_hi:[0,1,1]
	v_pk_mul_f32 v[20:21], v[36:37], v[20:21] op_sel_hi:[0,1]
	v_and_b32_e32 v19, 0xffff0000, v19
	v_and_b32_e32 v18, 0xffff0000, v18
	v_pk_mul_f32 v[22:23], v[24:25], v[22:23]
	v_pk_fma_f32 v[20:21], v[34:35], v[32:33], v[20:21] op_sel_hi:[0,1,1]
	v_pk_mul_f32 v[18:19], v[20:21], v[18:19]
	v_and_b32_sdwa v20, v23, v177 dst_sel:DWORD dst_unused:UNUSED_PAD src0_sel:WORD_1 src1_sel:DWORD
	v_and_b32_sdwa v21, v22, v177 dst_sel:DWORD dst_unused:UNUSED_PAD src0_sel:WORD_1 src1_sel:DWORD
	v_add3_u32 v21, v22, v21, s28
	v_add3_u32 v20, v23, v20, s28
	v_and_b32_sdwa v22, v19, v177 dst_sel:DWORD dst_unused:UNUSED_PAD src0_sel:WORD_1 src1_sel:DWORD
	v_and_b32_sdwa v23, v18, v177 dst_sel:DWORD dst_unused:UNUSED_PAD src0_sel:WORD_1 src1_sel:DWORD
	v_add3_u32 v19, v19, v22, s28
	v_add3_u32 v18, v18, v23, s28
	v_and_b32_e32 v19, 0xffff0000, v19
	v_and_b32_e32 v18, 0xffff0000, v18
	v_or_b32_sdwa v19, v19, v20 dst_sel:DWORD dst_unused:UNUSED_PAD src0_sel:DWORD src1_sel:WORD_1
	v_or_b32_sdwa v18, v18, v21 dst_sel:DWORD dst_unused:UNUSED_PAD src0_sel:DWORD src1_sel:WORD_1
	global_store_dwordx2 v[40:41], v[18:19], off offset:48
	s_and_saveexec_b64 s[6:7], s[44:45]
	s_xor_b64 s[6:7], exec, s[6:7]
	s_cbranch_execz .LBB0_961
	v_add_u32_e32 v18, 0x400, v38
	v_ashrrev_i32_e32 v19, 31, v18
	v_lshl_add_u64 v[18:19], v[0:1], 0, v[18:19]
	v_lshlrev_b64 v[18:19], 1, v[18:19]
	v_lshl_add_u64 v[20:21], s[16:17], 0, v[18:19]
	v_lshl_add_u64 v[22:23], s[46:47], 0, v[18:19]
	v_mov_b32_e32 v20, v156
	v_mov_b32_e32 v21, v157
	s_nop 0
	v_mov_b32_e32 v22, v154
	v_mov_b32_e32 v23, v155
	v_mov_b32_e32 v37, v36
	v_mov_b32_e32 v35, v34
	v_mov_b32_e32 v28, v2
	v_mov_b32_e32 v29, v4
	v_mov_b32_e32 v4, v3
	v_lshl_add_u64 v[18:19], s[18:19], 0, v[18:19]
	v_lshlrev_b32_e32 v25, 16, v21
	v_lshlrev_b32_e32 v27, 16, v23
	v_lshlrev_b32_e32 v26, 16, v22
	v_and_b32_e32 v23, 0xffff0000, v23
	v_and_b32_e32 v22, 0xffff0000, v22
	v_pk_mul_f32 v[2:3], v[36:37], v[22:23]
	v_lshlrev_b32_e32 v24, 16, v20
	v_and_b32_e32 v21, 0xffff0000, v21
	v_and_b32_e32 v20, 0xffff0000, v20
	v_pk_mul_f32 v[26:27], v[36:37], v[26:27]
	v_pk_fma_f32 v[2:3], v[34:35], v[4:5], v[2:3]
	v_pk_fma_f32 v[26:27], v[34:35], v[28:29], v[26:27]
	v_pk_mul_f32 v[2:3], v[2:3], v[20:21]
	v_pk_mul_f32 v[24:25], v[26:27], v[24:25]
	v_and_b32_sdwa v20, v3, v177 dst_sel:DWORD dst_unused:UNUSED_PAD src0_sel:WORD_1 src1_sel:DWORD
	v_and_b32_sdwa v21, v2, v177 dst_sel:DWORD dst_unused:UNUSED_PAD src0_sel:WORD_1 src1_sel:DWORD
	v_and_b32_sdwa v4, v25, v177 dst_sel:DWORD dst_unused:UNUSED_PAD src0_sel:WORD_1 src1_sel:DWORD
	v_and_b32_sdwa v5, v24, v177 dst_sel:DWORD dst_unused:UNUSED_PAD src0_sel:WORD_1 src1_sel:DWORD
	v_add3_u32 v3, v3, v20, s28
	v_add3_u32 v2, v2, v21, s28
	v_add3_u32 v5, v24, v5, s28
	v_add3_u32 v4, v25, v4, s28
	v_and_b32_e32 v3, 0xffff0000, v3
	v_and_b32_e32 v2, 0xffff0000, v2
	v_or_b32_sdwa v3, v3, v4 dst_sel:DWORD dst_unused:UNUSED_PAD src0_sel:DWORD src1_sel:WORD_1
	v_or_b32_sdwa v2, v2, v5 dst_sel:DWORD dst_unused:UNUSED_PAD src0_sel:DWORD src1_sel:WORD_1
	global_store_dwordx2 v[18:19], v[2:3], off
	v_add_u32_e32 v2, 0x408, v38
	v_ashrrev_i32_e32 v3, 31, v2
	v_lshl_add_u64 v[2:3], v[0:1], 0, v[2:3]
	v_lshlrev_b64 v[2:3], 1, v[2:3]
	v_lshl_add_u64 v[4:5], s[16:17], 0, v[2:3]
	v_lshl_add_u64 v[18:19], s[46:47], 0, v[2:3]
	v_mov_b32_e32 v4, v160
	v_mov_b32_e32 v5, v161
	s_nop 0
	v_mov_b32_e32 v18, v158
	v_mov_b32_e32 v19, v159
	v_mov_b32_e32 v24, v6
	v_mov_b32_e32 v25, v8
	v_mov_b32_e32 v8, v7
	v_lshl_add_u64 v[2:3], s[18:19], 0, v[2:3]
	v_lshlrev_b32_e32 v21, 16, v5
	v_lshlrev_b32_e32 v23, 16, v19
	v_lshlrev_b32_e32 v22, 16, v18
	v_and_b32_e32 v19, 0xffff0000, v19
	v_and_b32_e32 v18, 0xffff0000, v18
	v_pk_mul_f32 v[6:7], v[36:37], v[18:19]
	v_lshlrev_b32_e32 v20, 16, v4
	v_and_b32_e32 v5, 0xffff0000, v5
	v_and_b32_e32 v4, 0xffff0000, v4
	v_pk_mul_f32 v[22:23], v[36:37], v[22:23]
	v_pk_fma_f32 v[6:7], v[34:35], v[8:9], v[6:7]
	v_pk_fma_f32 v[22:23], v[34:35], v[24:25], v[22:23]
	v_pk_mul_f32 v[4:5], v[6:7], v[4:5]
	v_pk_mul_f32 v[20:21], v[22:23], v[20:21]
	v_and_b32_sdwa v8, v5, v177 dst_sel:DWORD dst_unused:UNUSED_PAD src0_sel:WORD_1 src1_sel:DWORD
	v_and_b32_sdwa v9, v4, v177 dst_sel:DWORD dst_unused:UNUSED_PAD src0_sel:WORD_1 src1_sel:DWORD
	v_and_b32_sdwa v6, v21, v177 dst_sel:DWORD dst_unused:UNUSED_PAD src0_sel:WORD_1 src1_sel:DWORD
	v_and_b32_sdwa v7, v20, v177 dst_sel:DWORD dst_unused:UNUSED_PAD src0_sel:WORD_1 src1_sel:DWORD
	v_add3_u32 v5, v5, v8, s28
	v_add3_u32 v4, v4, v9, s28
	v_add3_u32 v7, v20, v7, s28
	v_add3_u32 v6, v21, v6, s28
	v_and_b32_e32 v5, 0xffff0000, v5
	v_and_b32_e32 v4, 0xffff0000, v4
	v_or_b32_sdwa v5, v5, v6 dst_sel:DWORD dst_unused:UNUSED_PAD src0_sel:DWORD src1_sel:WORD_1
	v_or_b32_sdwa v4, v4, v7 dst_sel:DWORD dst_unused:UNUSED_PAD src0_sel:DWORD src1_sel:WORD_1
	global_store_dwordx2 v[2:3], v[4:5], off
	v_add_u32_e32 v2, 0x410, v38
	v_ashrrev_i32_e32 v3, 31, v2
	v_lshl_add_u64 v[2:3], v[0:1], 0, v[2:3]
	v_lshlrev_b64 v[2:3], 1, v[2:3]
	v_lshl_add_u64 v[4:5], s[16:17], 0, v[2:3]
	v_lshl_add_u64 v[6:7], s[46:47], 0, v[2:3]
	v_mov_b32_e32 v4, v164
	v_mov_b32_e32 v5, v165
	s_nop 0
	v_mov_b32_e32 v6, v162
	v_mov_b32_e32 v7, v163
	v_mov_b32_e32 v20, v10
	v_mov_b32_e32 v21, v12
	v_mov_b32_e32 v12, v11
	v_lshl_add_u64 v[2:3], s[18:19], 0, v[2:3]
	v_lshlrev_b32_e32 v9, 16, v5
	v_lshlrev_b32_e32 v19, 16, v7
	v_lshlrev_b32_e32 v18, 16, v6
	v_and_b32_e32 v7, 0xffff0000, v7
	v_and_b32_e32 v6, 0xffff0000, v6
	v_pk_mul_f32 v[18:19], v[36:37], v[18:19]
	v_lshlrev_b32_e32 v8, 16, v4
	v_pk_fma_f32 v[18:19], v[34:35], v[20:21], v[18:19]
	v_pk_mul_f32 v[6:7], v[36:37], v[6:7]
	v_and_b32_e32 v5, 0xffff0000, v5
	v_and_b32_e32 v4, 0xffff0000, v4
	v_pk_mul_f32 v[8:9], v[18:19], v[8:9]
	v_pk_fma_f32 v[6:7], v[34:35], v[12:13], v[6:7]
	v_mov_b32_e32 v12, v14
	v_pk_mul_f32 v[4:5], v[6:7], v[4:5]
	v_and_b32_sdwa v6, v9, v177 dst_sel:DWORD dst_unused:UNUSED_PAD src0_sel:WORD_1 src1_sel:DWORD
	v_and_b32_sdwa v7, v8, v177 dst_sel:DWORD dst_unused:UNUSED_PAD src0_sel:WORD_1 src1_sel:DWORD
	v_add3_u32 v7, v8, v7, s28
	v_add3_u32 v6, v9, v6, s28
	v_and_b32_sdwa v8, v5, v177 dst_sel:DWORD dst_unused:UNUSED_PAD src0_sel:WORD_1 src1_sel:DWORD
	v_and_b32_sdwa v9, v4, v177 dst_sel:DWORD dst_unused:UNUSED_PAD src0_sel:WORD_1 src1_sel:DWORD
	v_add3_u32 v5, v5, v8, s28
	v_add3_u32 v4, v4, v9, s28
	v_and_b32_e32 v5, 0xffff0000, v5
	v_and_b32_e32 v4, 0xffff0000, v4
	v_or_b32_sdwa v5, v5, v6 dst_sel:DWORD dst_unused:UNUSED_PAD src0_sel:DWORD src1_sel:WORD_1
	v_or_b32_sdwa v4, v4, v7 dst_sel:DWORD dst_unused:UNUSED_PAD src0_sel:DWORD src1_sel:WORD_1
	global_store_dwordx2 v[2:3], v[4:5], off
	v_add_u32_e32 v2, 0x418, v38
	v_ashrrev_i32_e32 v3, 31, v2
	v_lshl_add_u64 v[2:3], v[0:1], 0, v[2:3]
	v_lshlrev_b64 v[2:3], 1, v[2:3]
	v_lshl_add_u64 v[4:5], s[16:17], 0, v[2:3]
	v_lshl_add_u64 v[6:7], s[46:47], 0, v[2:3]
	v_mov_b32_e32 v4, v168
	v_mov_b32_e32 v5, v169
	s_nop 0
	v_mov_b32_e32 v6, v166
	v_mov_b32_e32 v7, v167
	v_mov_b32_e32 v13, v16
	v_mov_b32_e32 v16, v15
	v_lshl_add_u64 v[2:3], s[18:19], 0, v[2:3]
	v_lshlrev_b32_e32 v9, 16, v5
	v_lshlrev_b32_e32 v11, 16, v7
	v_lshlrev_b32_e32 v10, 16, v6
	v_and_b32_e32 v7, 0xffff0000, v7
	v_and_b32_e32 v6, 0xffff0000, v6
	v_pk_mul_f32 v[10:11], v[36:37], v[10:11]
	v_lshlrev_b32_e32 v8, 16, v4
	v_pk_fma_f32 v[10:11], v[34:35], v[12:13], v[10:11]
	v_pk_mul_f32 v[6:7], v[36:37], v[6:7]
	v_and_b32_e32 v5, 0xffff0000, v5
	v_and_b32_e32 v4, 0xffff0000, v4
	v_pk_mul_f32 v[8:9], v[10:11], v[8:9]
	v_pk_fma_f32 v[6:7], v[34:35], v[16:17], v[6:7]
	v_and_b32_sdwa v0, v9, v177 dst_sel:DWORD dst_unused:UNUSED_PAD src0_sel:WORD_1 src1_sel:DWORD
	v_pk_mul_f32 v[4:5], v[6:7], v[4:5]
	v_and_b32_sdwa v6, v8, v177 dst_sel:DWORD dst_unused:UNUSED_PAD src0_sel:WORD_1 src1_sel:DWORD
	v_add3_u32 v6, v8, v6, s28
	v_and_b32_sdwa v7, v5, v177 dst_sel:DWORD dst_unused:UNUSED_PAD src0_sel:WORD_1 src1_sel:DWORD
	v_and_b32_sdwa v8, v4, v177 dst_sel:DWORD dst_unused:UNUSED_PAD src0_sel:WORD_1 src1_sel:DWORD
	v_add3_u32 v5, v5, v7, s28
	v_add3_u32 v4, v4, v8, s28
	v_add3_u32 v0, v9, v0, s28
	v_and_b32_e32 v5, 0xffff0000, v5
	v_and_b32_e32 v4, 0xffff0000, v4
	v_or_b32_sdwa v5, v5, v0 dst_sel:DWORD dst_unused:UNUSED_PAD src0_sel:DWORD src1_sel:WORD_1
	v_or_b32_sdwa v4, v4, v6 dst_sel:DWORD dst_unused:UNUSED_PAD src0_sel:DWORD src1_sel:WORD_1
	global_store_dwordx2 v[2:3], v[4:5], off
	s_branch .LBB0_961
